# v74 plus attention loop: scalar compare chain for the per-tile vmcnt wait choice instead of nested exec-mask ladders; two 0+y sum inits dropped
# speedup vs baseline: 1.0027x; 1.0004x over previous
.LBB0_275:
	s_or_b64 exec, exec, s[36:37]
	v_add_u32_e32 v0, s52, v121
	s_nop 0
	v_readfirstlane_b32 s36, v0
	s_cmp_gt_i32 s36, 3
	s_cbranch_scc1 .Lvw8
	s_cmp_gt_i32 s36, 1
	s_cbranch_scc0 .Lvw_lo
	s_cmp_eq_u32 s36, 3
	s_cbranch_scc1 .Lvw6
	s_waitcnt vmcnt(4)
	s_branch .LBB0_291
.Lvw6:
	s_waitcnt vmcnt(6)
	s_branch .LBB0_291
.Lvw_lo:
	s_cmp_eq_u32 s36, 1
	s_cbranch_scc1 .Lvw2
	s_waitcnt vmcnt(0)
	s_branch .LBB0_291
.Lvw2:
	s_waitcnt vmcnt(2)
	s_branch .LBB0_291
.Lvw8:
	s_waitcnt vmcnt(8)
.LBB0_291:
	s_mul_hi_u32 s36, s54, 0xaaaaaaab
	s_lshr_b32 s36, s36, 2
	s_mul_i32 s36, s36, 0x18000
	s_sub_i32 s32, s53, s36
	s_barrier
	v_cmp_ge_i32_e32 vcc, s54, v123
	s_or_b64 s[36:37], s[48:49], vcc
	s_and_saveexec_b64 s[44:45], s[36:37]
	s_xor_b64 s[36:37], exec, s[44:45]
	s_cbranch_execz .LBB0_295
	v_add_u32_e32 v5, s32, v163
	v_add_u32_e32 v4, v5, v115
	v_add_u32_e32 v185, v5, v127
	v_add_u32_e32 v187, v5, v128
	v_add_u32_e32 v0, v5, v129
	ds_read_b128 v[8:11], v4
	ds_read_b128 v[12:15], v4 offset:4096
	ds_read_b128 v[96:99], v185
	ds_read_b128 v[188:191], v185 offset:4096
	ds_read_b128 v[192:195], v187
	ds_read_b128 v[196:199], v187 offset:4096
	ds_read_b128 v[226:229], v0
	ds_read_b128 v[230:233], v0 offset:4096
	s_waitcnt lgkmcnt(7)
	v_mfma_f32_32x32x16_f16 v[48:63], v[8:11], v[88:91], 0
	s_waitcnt lgkmcnt(6)
	v_mfma_f32_32x32x16_f16 v[64:79], v[12:15], v[88:91], 0
	s_waitcnt lgkmcnt(5)
	v_mfma_f32_32x32x16_f16 v[48:63], v[96:99], v[80:83], v[48:63]
	s_waitcnt lgkmcnt(4)
	v_mfma_f32_32x32x16_f16 v[64:79], v[188:191], v[80:83], v[64:79]
	s_waitcnt lgkmcnt(3)
	v_mfma_f32_32x32x16_f16 v[48:63], v[192:195], v[84:87], v[48:63]
	s_waitcnt lgkmcnt(2)
	v_mfma_f32_32x32x16_f16 v[64:79], v[196:199], v[84:87], v[64:79]
	s_waitcnt lgkmcnt(1)
	v_mfma_f32_32x32x16_f16 v[48:63], v[226:229], v[92:95], v[48:63]
	s_waitcnt lgkmcnt(0)
	v_mfma_f32_32x32x16_f16 v[64:79], v[230:233], v[92:95], v[64:79]
	s_nop 11
	v_max3_f32 v0, v48, s55, v64
	v_max3_f32 v0, v0, v49, v65
	v_max3_f32 v0, v0, v50, v66
	v_max3_f32 v0, v0, v51, v67
	v_max3_f32 v0, v0, v52, v68
	v_max3_f32 v0, v0, v53, v69
	v_max3_f32 v0, v0, v54, v70
	v_max3_f32 v0, v0, v55, v71
	v_max3_f32 v0, v0, v56, v72
	v_max3_f32 v0, v0, v57, v73
	v_max3_f32 v0, v0, v58, v74
	v_max3_f32 v0, v0, v59, v75
	v_max3_f32 v0, v0, v60, v76
	v_max3_f32 v0, v0, v61, v77
	v_max3_f32 v0, v0, v62, v78
	v_max3_f32 v0, v0, v63, v79
	v_mov_b32_e32 v4, v0
	s_nop 1
	v_permlane32_swap_b32_e32 v0, v4
	v_max3_f32 v4, v186, v0, v4
	v_sub_f32_e32 v0, v186, v4
	v_exp_f32_e32 v0, v0
	s_nop 0
	v_cmp_neq_f32_e32 vcc, 1.0, v0
	s_cbranch_vccz .LBB0_294
	v_mul_f32_e32 v30, v0, v30
	v_mul_f32_e32 v31, v0, v31
	v_mul_f32_e32 v28, v0, v28
	v_mul_f32_e32 v29, v0, v29
	v_mul_f32_e32 v26, v0, v26
	v_mul_f32_e32 v27, v0, v27
	v_mul_f32_e32 v24, v0, v24
	v_mul_f32_e32 v25, v0, v25
	v_mul_f32_e32 v22, v0, v22
	v_mul_f32_e32 v23, v0, v23
	v_mul_f32_e32 v20, v0, v20
	v_mul_f32_e32 v21, v0, v21
	v_mul_f32_e32 v18, v0, v18
	v_mul_f32_e32 v19, v0, v19
	v_mul_f32_e32 v16, v0, v16
	v_mul_f32_e32 v17, v0, v17
	v_mul_f32_e32 v46, v0, v46
	v_mul_f32_e32 v47, v0, v47
	v_mul_f32_e32 v44, v0, v44
	v_mul_f32_e32 v45, v0, v45
	v_mul_f32_e32 v42, v0, v42
	v_mul_f32_e32 v43, v0, v43
	v_mul_f32_e32 v40, v0, v40
	v_mul_f32_e32 v41, v0, v41
	v_mul_f32_e32 v38, v0, v38
	v_mul_f32_e32 v39, v0, v39
	v_mul_f32_e32 v36, v0, v36
	v_mul_f32_e32 v37, v0, v37
	v_mul_f32_e32 v34, v0, v34
	v_mul_f32_e32 v35, v0, v35
	v_mul_f32_e32 v32, v0, v32
	v_mul_f32_e32 v33, v0, v33
.LBB0_294:
	v_sub_f32_e32 v10, v65, v4
	v_exp_f32_e32 v15, v10
	v_sub_f32_e32 v10, v50, v4
	v_sub_f32_e32 v50, v71, v4
	v_sub_f32_e32 v6, v48, v4
	v_sub_f32_e32 v8, v64, v4
	v_sub_f32_e32 v48, v69, v4
	v_exp_f32_e32 v69, v50
	v_sub_f32_e32 v50, v56, v4
	v_exp_f32_e32 v6, v6
	v_exp_f32_e32 v14, v8
	v_sub_f32_e32 v9, v49, v4
	v_exp_f32_e32 v56, v50
	v_sub_f32_e32 v50, v72, v4
	v_exp_f32_e32 v9, v9
	v_sub_f32_e32 v11, v66, v4
	v_sub_f32_e32 v49, v70, v4
	v_exp_f32_e32 v70, v50
	v_sub_f32_e32 v50, v57, v4
	v_exp_f32_e32 v10, v10
	v_exp_f32_e32 v64, v11
	v_sub_f32_e32 v11, v51, v4
	v_sub_f32_e32 v12, v67, v4
	v_exp_f32_e32 v57, v50
	v_sub_f32_e32 v50, v73, v4
	v_exp_f32_e32 v11, v11
	v_exp_f32_e32 v65, v12
	v_sub_f32_e32 v12, v52, v4
	v_sub_f32_e32 v13, v68, v4
	v_exp_f32_e32 v71, v50
	v_sub_f32_e32 v50, v58, v4
	v_exp_f32_e32 v12, v12
	v_exp_f32_e32 v66, v13
	v_sub_f32_e32 v13, v53, v4
	v_exp_f32_e32 v58, v50
	v_sub_f32_e32 v50, v74, v4
	v_add_f32_e32 v7, v9, v6
	v_add_f32_e32 v8, v15, v14
	v_exp_f32_e32 v13, v13
	v_exp_f32_e32 v67, v48
	v_sub_f32_e32 v48, v54, v4
	v_exp_f32_e32 v72, v50
	v_sub_f32_e32 v50, v59, v4
	v_add_f32_e32 v7, v10, v7
	v_add_f32_e32 v8, v64, v8
	v_exp_f32_e32 v48, v48
	v_exp_f32_e32 v68, v49
	v_sub_f32_e32 v49, v55, v4
	v_exp_f32_e32 v73, v50
	v_sub_f32_e32 v50, v75, v4
	v_add_f32_e32 v7, v11, v7
	v_add_f32_e32 v8, v65, v8
	v_exp_f32_e32 v49, v49
	v_exp_f32_e32 v74, v50
	v_sub_f32_e32 v50, v60, v4
	v_add_f32_e32 v7, v12, v7
	v_add_f32_e32 v8, v66, v8
	v_exp_f32_e32 v60, v50
	v_sub_f32_e32 v50, v76, v4
	v_add_f32_e32 v7, v13, v7
	v_add_f32_e32 v8, v67, v8
	v_exp_f32_e32 v75, v50
	v_sub_f32_e32 v50, v61, v4
	v_add_f32_e32 v7, v48, v7
	v_add_f32_e32 v8, v68, v8
	v_exp_f32_e32 v61, v50
	v_sub_f32_e32 v50, v77, v4
	v_add_f32_e32 v7, v49, v7
	v_add_f32_e32 v8, v69, v8
	v_exp_f32_e32 v76, v50
	v_sub_f32_e32 v50, v62, v4
	v_add_f32_e32 v7, v56, v7
	v_add_f32_e32 v8, v70, v8
	v_exp_f32_e32 v62, v50
	v_sub_f32_e32 v50, v78, v4
	v_add_f32_e32 v7, v57, v7
	v_add_f32_e32 v8, v71, v8
	v_exp_f32_e32 v77, v50
	v_sub_f32_e32 v50, v63, v4
	v_add_f32_e32 v7, v58, v7
	v_add_f32_e32 v8, v72, v8
	v_exp_f32_e32 v63, v50
	v_sub_f32_e32 v50, v79, v4
	v_add_f32_e32 v7, v73, v7
	v_add_f32_e32 v8, v74, v8
	v_exp_f32_e32 v78, v50
	v_add_f32_e32 v7, v60, v7
	v_add_f32_e32 v8, v75, v8
	v_add_f32_e32 v7, v61, v7
	v_add_f32_e32 v8, v76, v8
	v_add_f32_e32 v7, v62, v7
	v_add_f32_e32 v8, v77, v8
	v_add_f32_e32 v7, v63, v7
	v_add_f32_e32 v8, v78, v8
	v_add_f32_e32 v59, v8, v7
	v_fmac_f32_e32 v59, v177, v0
	v_cvt_pkrtz_f16_f32 v7, v10, v11
	v_cvt_pkrtz_f16_f32 v8, v12, v13
	v_cvt_pkrtz_f16_f32 v6, v6, v9
	v_cvt_pkrtz_f16_f32 v9, v48, v49
	v_add_u32_e32 v0, v5, v172
	v_add_u32_e32 v196, v5, v170
	ds_read_b64 v[52:53], v0
	ds_read_b64 v[48:49], v0 offset:4096
	ds_read_b64 v[54:55], v196
	ds_read_b64 v[50:51], v196 offset:4096
	v_add_u32_e32 v0, v5, v169
	v_add_u32_e32 v196, v5, v168
	ds_read_b64 v[192:193], v0
	ds_read_b64 v[188:189], v0 offset:4096
	ds_read_b64 v[194:195], v196
	ds_read_b64 v[190:191], v196 offset:4096
	v_cvt_pkrtz_f16_f32 v10, v56, v57
	v_cvt_pkrtz_f16_f32 v11, v58, v73
	v_cvt_pkrtz_f16_f32 v12, v60, v61
	v_cvt_pkrtz_f16_f32 v13, v62, v63
	s_waitcnt lgkmcnt(4)
	v_mfma_f32_32x32x16_f16 v[32:47], v[48:51], v[6:9], v[32:47]
	v_mfma_f32_32x32x16_f16 v[16:31], v[52:55], v[6:9], v[16:31]
	v_add_u32_e32 v0, v5, v166
	v_add_u32_e32 v196, v5, v164
	ds_read_b64 v[52:53], v0
	ds_read_b64 v[48:49], v0 offset:4096
	ds_read_b64 v[54:55], v196 offset:8192
	ds_read_b64 v[50:51], v196 offset:12288
	v_cvt_pkrtz_f16_f32 v6, v14, v15
	v_cvt_pkrtz_f16_f32 v7, v64, v65
	v_cvt_pkrtz_f16_f32 v8, v66, v67
	v_cvt_pkrtz_f16_f32 v9, v68, v69
	s_waitcnt lgkmcnt(4)
	v_mfma_f32_32x32x16_f16 v[32:47], v[188:191], v[10:13], v[32:47]
	v_mfma_f32_32x32x16_f16 v[16:31], v[192:195], v[10:13], v[16:31]
	v_add_u32_e32 v0, v5, v175
	v_add_u32_e32 v196, v5, v173
	ds_read_b64 v[192:193], v0
	ds_read_b64 v[188:189], v0 offset:4096
	ds_read_b64 v[194:195], v196
	ds_read_b64 v[190:191], v196 offset:4096
	v_cvt_pkrtz_f16_f32 v13, v77, v78
	v_cvt_pkrtz_f16_f32 v10, v70, v71
	v_cvt_pkrtz_f16_f32 v11, v72, v74
	v_cvt_pkrtz_f16_f32 v12, v75, v76
	s_waitcnt lgkmcnt(4)
	v_mfma_f32_32x32x16_f16 v[32:47], v[48:51], v[6:9], v[32:47]
	v_mfma_f32_32x32x16_f16 v[16:31], v[52:55], v[6:9], v[16:31]
	s_waitcnt lgkmcnt(0)
	v_mfma_f32_32x32x16_f16 v[32:47], v[188:191], v[10:13], v[32:47]
	v_mfma_f32_32x32x16_f16 v[16:31], v[192:195], v[10:13], v[16:31]
